# HGRN main phase: flat loads/stores converted to global (lgkmcnt waits no longer drain the global prefetch)
# baseline (speedup 1.0000x reference)
.LBB0_583:
	s_and_b64 vcc, exec, s[0:1]
	s_cbranch_vccz .LBB0_747
	v_readlane_b32 s0, v244, 0
	v_readlane_b32 s1, v244, 1
	s_mov_b64 s[6:7], s[46:47]
	v_mov_b32_e32 v58, v194
	s_andn2_b64 vcc, exec, s[0:1]
	s_cbranch_vccnz .LBB0_610
	s_add_u32 s4, s6, 0xd200000
	s_addc_u32 s5, s7, 0
	s_add_u32 s8, s6, 0x16200000
	v_readlane_b32 s0, v244, 2
	s_addc_u32 s9, s7, 0
	v_and_b32_e32 v0, 0x7f, v58
	v_readlane_b32 s1, v244, 3
	s_add_u32 s10, s6, 0x10200000
	v_ashrrev_i32_e32 v43, 7, v58
	v_or_b32_e32 v40, s0, v0
	v_mov_b32_e32 v41, s1
	v_readlane_b32 s0, v243, 25
	v_readlane_b32 s1, v244, 5
	s_addc_u32 s11, s7, 0
	v_lshlrev_b32_e32 v1, 3, v43
	s_add_i32 s0, s1, s0
	v_add_u32_e32 v2, s0, v1
	s_movk_i32 s0, 0x300
	v_mad_i64_i32 v[10:11], s[0:1], v2, s0, v[40:41]
	v_lshl_add_u64 v[14:15], v[10:11], 2, s[8:9]
	s_movk_i32 s0, 0x1000
	v_lshlrev_b64 v[4:5], 1, v[10:11]
	v_add_co_u32_e32 v6, vcc, s0, v14
	v_lshl_add_u64 v[16:17], s[4:5], 0, v[4:5]
	v_lshl_add_u64 v[38:39], s[10:11], 0, v[4:5]
	v_addc_co_u32_e32 v7, vcc, 0, v15, vcc
	global_load_dword v32, v[14:15], off
	global_load_ushort v31, v[16:17], off
	global_load_ushort v4, v[38:39], off
	global_load_dword v30, v[14:15], off offset:3072
	global_load_ushort v28, v[16:17], off offset:1536
	global_load_ushort v12, v[38:39], off offset:1536
	global_load_dword v23, v[6:7], off offset:2048
	global_load_ushort v21, v[16:17], off offset:3072
	global_load_ushort v5, v[38:39], off offset:3072
	v_add_co_u32_e32 v6, vcc, s36, v14
	s_movk_i32 s12, 0x7f
	s_nop 0
	v_addc_co_u32_e32 v7, vcc, 0, v15, vcc
	v_add_co_u32_e32 v8, vcc, s0, v16
	global_load_dword v26, v[6:7], off offset:1024
	s_nop 0
	v_addc_co_u32_e32 v9, vcc, 0, v17, vcc
	v_add_co_u32_e32 v18, vcc, s0, v38
	s_movk_i32 s0, 0x3000
	s_nop 0
	v_addc_co_u32_e32 v19, vcc, 0, v39, vcc
	v_add_co_u32_e32 v36, vcc, s0, v14
	s_movk_i32 s0, 0x4000
	s_nop 0
	v_addc_co_u32_e32 v37, vcc, 0, v15, vcc
	global_load_ushort v27, v[8:9], off offset:512
	global_load_ushort v34, v[18:19], off offset:512
	global_load_dword v24, v[36:37], off
	global_load_ushort v29, v[8:9], off offset:2048
	global_load_ushort v6, v[18:19], off offset:2048
	global_load_dword v22, v[36:37], off offset:3072
	s_nop 0
	global_load_ushort v8, v[8:9], off offset:3584
	s_nop 0
	global_load_ushort v36, v[18:19], off offset:3584
	v_add_co_u32_e32 v18, vcc, s0, v14
	s_movk_i32 s0, 0x5000
	s_nop 0
	v_addc_co_u32_e32 v19, vcc, 0, v15, vcc
	v_add_co_u32_e32 v16, vcc, s36, v16
	global_load_dword v18, v[18:19], off offset:2048
	s_nop 0
	v_addc_co_u32_e32 v17, vcc, 0, v17, vcc
	v_add_co_u32_e32 v38, vcc, s36, v38
	v_readfirstlane_b32 s18, v58
	s_nop 0
	v_addc_co_u32_e32 v39, vcc, 0, v39, vcc
	v_add_co_u32_e32 v14, vcc, s0, v14
	global_load_ushort v7, v[38:39], off offset:1024
	global_load_ushort v2, v[16:17], off offset:1024
	v_addc_co_u32_e32 v15, vcc, 0, v15, vcc
	global_load_dword v20, v[14:15], off offset:1024
	global_load_ushort v19, v[16:17], off offset:2560
	global_load_ushort v44, v[38:39], off offset:2560
	v_readlane_b32 s0, v243, 43
	s_movk_i32 s19, 0x1000
	v_mov_b32_e32 v9, 0
	v_lshl_add_u32 v59, v58, 2, s0
	v_lshl_add_u32 v61, v0, 2, s0
	s_movk_i32 s0, 0x80
	v_cmp_gt_u32_e64 s[0:1], s0, v58
	v_cmp_lt_u32_e32 vcc, s12, v58
	s_waitcnt vmcnt(0) lgkmcnt(0)
	v_add_f32_e32 v42, 0, v32
	v_add_f32_e32 v39, v42, v30
	v_add_f32_e32 v38, v39, v23
	v_add_f32_e32 v37, v38, v26
	v_add_f32_e32 v35, v37, v24
	v_add_f32_e32 v33, v35, v22
	v_add_f32_e32 v13, v33, v18
	v_add_f32_e32 v25, v13, v20
	ds_write_b32 v59, v25
	s_waitcnt lgkmcnt(0)
	s_barrier
	ds_read2st64_b32 v[16:17], v61 offset1:2
	ds_read2st64_b32 v[14:15], v61 offset0:4 offset1:6
	s_and_saveexec_b64 s[12:13], vcc
	s_cbranch_execz .LBB0_591
	v_cmp_lt_i32_e64 s[40:41], 1, v43
	s_mov_b64 s[14:15], 0
	s_and_saveexec_b64 s[16:17], s[40:41]
	s_xor_b64 s[28:29], exec, s[16:17]
	s_cbranch_execnz .LBB0_644
	s_andn2_saveexec_b64 s[28:29], s[28:29]
	s_cbranch_execnz .LBB0_647

.LBB0_594:
	s_or_b64 exec, exec, s[14:15]
	ds_read_b128 v[36:39], v66
	ds_read_b128 v[54:57], v66 offset:16
	v_ashrrev_i32_e32 v51, 31, v50
	s_add_i32 s13, s13, 1
	v_lshlrev_b64 v[0:1], 11, v[50:51]
	v_readlane_b32 s38, v243, 62
	v_readlane_b32 s50, v242, 0
	v_add_f32_e32 v47, v47, v52
	v_lshl_add_u64 v[0:1], v[44:45], 0, v[0:1]
	v_add_u32_e32 v50, 32, v50
	s_cmp_eq_u32 s13, 31
	v_add_u32_e32 v79, 32, v79
	v_readlane_b32 s39, v243, 63
	v_readlane_b32 s51, v242, 1
	s_waitcnt lgkmcnt(1)
	v_cvt_pk_bf16_f32 v36, v36, v37
	v_cvt_pk_bf16_f32 v37, v38, v39
	s_waitcnt lgkmcnt(0)
	v_cvt_pk_bf16_f32 v38, v54, v55
	v_cvt_pk_bf16_f32 v39, v56, v57
	global_store_dwordx4 v[0:1], v[36:39], off
	s_waitcnt lgkmcnt(0)
	s_barrier
	s_cbranch_scc1 .LBB0_607
.LBB0_595:
	s_movk_i32 s14, 0x300
	v_mad_i64_i32 v[36:37], s[14:15], v79, s14, v[40:41]
	v_lshlrev_b64 v[38:39], 1, v[36:37]
	s_mov_b64 s[14:15], 0x300
	v_lshl_add_u64 v[138:139], s[4:5], 0, v[38:39]
	v_lshl_add_u64 v[142:143], s[10:11], 0, v[38:39]
	v_lshl_add_u64 v[38:39], v[36:37], 0, s[14:15]
	s_mov_b64 s[14:15], 0x600
	s_and_b32 s18, s13, 1
	v_lshl_add_u64 v[0:1], v[36:37], 2, s[8:9]
	v_lshl_add_u64 v[36:37], v[36:37], 0, s[14:15]
	v_lshlrev_b64 v[88:89], 1, v[36:37]
	s_mul_i32 s14, s18, 0x9600
	v_lshl_add_u64 v[52:53], v[38:39], 2, s[8:9]
	v_lshlrev_b64 v[38:39], 1, v[38:39]
	v_lshl_add_u64 v[80:81], s[4:5], 0, v[88:89]
	s_add_i32 s14, s14, 0
	v_lshl_add_u64 v[54:55], s[4:5], 0, v[38:39]
	v_lshl_add_u64 v[38:39], s[10:11], 0, v[38:39]
	v_lshl_add_u64 v[56:57], v[36:37], 2, s[8:9]
	global_load_dword v90, v[0:1], off
	global_load_ushort v86, v[138:139], off
	global_load_ushort v36, v[142:143], off
	global_load_dword v85, v[52:53], off
	global_load_ushort v84, v[54:55], off
	s_nop 0
	global_load_ushort v52, v[38:39], off
	global_load_dword v82, v[56:57], off
	s_nop 0
	global_load_ushort v81, v[80:81], off
	v_lshl_add_u32 v53, v67, 1, s14
	v_lshl_add_u32 v2, v78, 1, v53
	ds_read_b128 v[54:57], v2 offset:8704
	ds_read_b128 v[98:101], v2 offset:4352
	ds_read_b128 v[102:105], v2 offset:8768
	v_lshl_add_u64 v[38:39], s[10:11], 0, v[88:89]
	v_add_co_u32_e64 v88, s[50:51], s36, v0
	s_movk_i32 s15, 0x1000
	s_nop 0
	v_addc_co_u32_e64 v89, s[50:51], 0, v1, s[50:51]
	ds_read_b128 v[106:109], v2 offset:4416
	v_add_co_u32_e64 v122, s[50:51], s15, v138
	s_waitcnt lgkmcnt(0)
	v_mfma_f32_16x16x32_bf16 v[92:95], v[54:57], v[98:101], 0
	v_addc_co_u32_e64 v123, s[50:51], 0, v139, s[50:51]
	v_add_co_u32_e64 v96, s[50:51], s15, v142
	s_movk_i32 s15, 0x3000
	s_nop 0
	v_addc_co_u32_e64 v97, s[50:51], 0, v143, s[50:51]
	v_add_co_u32_e64 v144, s[50:51], s15, v0
	v_mfma_f32_16x16x32_bf16 v[110:113], v[102:105], v[106:109], v[92:95]
	ds_read_b128 v[114:117], v2 offset:8832
	ds_read_b128 v[118:121], v2 offset:4480
	global_load_ushort v37, v[38:39], off
	global_load_dword v91, v[88:89], off offset:1024
	s_nop 0
	global_load_ushort v88, v[122:123], off offset:512
	global_load_ushort v95, v[96:97], off offset:512
	global_load_ushort v83, v[122:123], off offset:2048
	global_load_ushort v38, v[96:97], off offset:2048
	s_nop 0
	global_load_ushort v96, v[96:97], off offset:3584
	s_nop 0
	global_load_ushort v51, v[122:123], off offset:3584
	ds_read_b128 v[122:125], v2 offset:8896
	ds_read_b128 v[126:129], v2 offset:4544
	ds_read_b128 v[130:133], v2 offset:13056
	ds_read_b128 v[134:137], v2
	v_addc_co_u32_e64 v145, s[50:51], 0, v1, s[50:51]
	s_movk_i32 s15, 0x4000
	v_add_co_u32_e64 v92, s[50:51], s15, v0
	s_waitcnt lgkmcnt(0)
	v_mfma_f32_16x16x32_bf16 v[54:57], v[54:57], v[134:137], 0
	v_addc_co_u32_e64 v93, s[50:51], 0, v1, s[50:51]
	v_add_co_u32_e64 v146, s[50:51], s36, v138
	ds_read_b128 v[134:137], v2 offset:13120
	s_nop 0
	v_addc_co_u32_e64 v147, s[50:51], 0, v139, s[50:51]
	ds_read_b128 v[138:141], v2 offset:64
	v_add_co_u32_e64 v142, s[50:51], s36, v142
	v_mfma_f32_16x16x32_bf16 v[130:133], v[130:133], v[98:101], 0
	s_nop 0
	v_addc_co_u32_e64 v143, s[50:51], 0, v143, s[50:51]
	s_movk_i32 s15, 0x5000
	v_add_co_u32_e64 v0, s[50:51], s15, v0
	s_waitcnt lgkmcnt(0)
	v_mfma_f32_16x16x32_bf16 v[54:57], v[102:105], v[138:141], v[54:57]
	v_addc_co_u32_e64 v1, s[50:51], 0, v1, s[50:51]
	global_load_dword v97, v[144:145], off
	global_load_dword v94, v[144:145], off offset:3072
	s_nop 0
	global_load_dword v93, v[92:93], off offset:2048
	s_nop 0
	global_load_ushort v92, v[146:147], off offset:1024
	global_load_ushort v39, v[142:143], off offset:1024
	global_load_dword v89, v[0:1], off offset:1024
	global_load_ushort v98, v[142:143], off offset:2560
	global_load_ushort v87, v[146:147], off offset:2560
	ds_read_b128 v[100:103], v2 offset:13184
	ds_read_b128 v[138:141], v2 offset:128
	v_mfma_f32_16x16x32_bf16 v[104:107], v[134:137], v[106:109], v[130:133]
	s_nop 2
	ds_read_b128 v[130:133], v2 offset:13248
	ds_read_b128 v[134:137], v2 offset:192
	v_add_u32_e32 v0, v2, v75
	v_cvt_pk_bf16_f32 v142, v32, v33
	v_mfma_f32_16x16x32_bf16 v[110:113], v[114:117], v[118:121], v[110:113]
	v_cvt_pk_bf16_f32 v143, v34, v35
	v_cvt_pk_bf16_f32 v144, v24, v25
	v_cvt_pk_bf16_f32 v145, v26, v27
	s_waitcnt lgkmcnt(0)
	v_mfma_f32_16x16x32_bf16 v[54:57], v[114:117], v[138:141], v[54:57]
	v_add_u32_e32 v1, 0x1000, v0
	ds_read2_b64 v[114:117], v1 offset0:32 offset1:36
	s_movk_i32 s19, 0x1000
	v_mfma_f32_16x16x32_bf16 v[100:103], v[100:103], v[118:121], v[104:107]
	s_nop 2
	ds_read2_b64 v[104:107], v0 offset1:4
	v_mfma_f32_16x16x32_bf16 v[110:113], v[122:125], v[126:129], v[110:113]
	v_cvt_pk_bf16_f32 v118, v16, v17
	v_cvt_pk_bf16_f32 v119, v18, v19
	v_cvt_pk_bf16_f32 v120, v12, v13
	v_mfma_f32_16x16x32_bf16 v[54:57], v[122:125], v[134:137], v[54:57]
	v_cvt_pk_bf16_f32 v121, v14, v15
	ds_read2_b64 v[122:125], v0 offset0:8 offset1:12
	v_mfma_f32_16x16x32_bf16 v[100:103], v[130:133], v[126:129], v[100:103]
	ds_read2_b64 v[126:129], v1 offset0:40 offset1:44
	v_cvt_pk_bf16_f32 v130, v28, v29
	v_cvt_pk_bf16_f32 v131, v30, v31
	s_waitcnt lgkmcnt(0)
	v_mfma_f32_16x16x32_bf16 v[104:107], v[104:107], v[142:145], 0
	v_cvt_pk_bf16_f32 v132, v4, v5
	v_cvt_pk_bf16_f32 v133, v6, v7
	ds_read2_b64 v[134:137], v0 offset0:16 offset1:20
	v_mfma_f32_16x16x32_bf16 v[114:117], v[114:117], v[142:145], 0
	s_nop 2
	v_cndmask_b32_e64 v80, v100, 0, s[46:47]
	v_cndmask_b32_e64 v100, v57, 0, s[42:43]
	v_cndmask_b32_e64 v99, 0, v101, s[44:45]
	v_mfma_f32_16x16x32_bf16 v[104:107], v[122:125], v[118:121], v[104:107]
	ds_read2_b64 v[122:125], v1 offset0:48 offset1:52
	v_cvt_pk_bf16_f32 v138, v8, v9
	v_cvt_pk_bf16_f32 v139, v10, v11
	v_mfma_f32_16x16x32_bf16 v[114:117], v[126:129], v[118:121], v[114:117]
	v_cvt_pk_bf16_f32 v140, v20, v21
	v_cvt_pk_bf16_f32 v141, v22, v23
	ds_read2_b64 v[118:121], v0 offset0:24 offset1:28
	ds_read2_b64 v[126:129], v1 offset0:56 offset1:60
	v_cndmask_b32_e64 v0, v54, 0, s[46:47]
	v_cndmask_b32_e64 v1, 0, v55, s[44:45]
	s_waitcnt lgkmcnt(0)
	v_mfma_f32_16x16x32_bf16 v[104:107], v[134:137], v[130:133], v[104:107]
	v_cndmask_b32_e64 v2, v56, 0, s[40:41]
	v_cndmask_b32_e64 v108, v102, 0, s[40:41]
	v_cvt_pk_bf16_f32 v0, v0, v1
	v_mfma_f32_16x16x32_bf16 v[114:117], v[122:125], v[130:133], v[114:117]
	v_cvt_pk_bf16_f32 v1, v2, v100
	v_cvt_pk_bf16_f32 v100, v110, v111
	v_cvt_pk_bf16_f32 v101, v112, v113
	v_cvt_pk_bf16_f32 v102, v80, v99
	v_lshlrev_b32_e32 v80, 1, v68
	v_cndmask_b32_e64 v103, v103, 0, s[42:43]
	v_add3_u32 v99, s14, v69, v80
	v_cvt_pk_bf16_f32 v103, v108, v103
	v_add_u32_e32 v108, 0x6800, v99
	v_mov_b32_e32 v2, v3
	ds_read2_b64 v[108:111], v108 offset0:128 offset1:132
	v_mfma_f32_16x16x32_bf16 v[104:107], v[118:121], v[138:141], v[104:107]
	v_mfma_f32_16x16x32_bf16 v[54:57], v[126:129], v[138:141], v[114:117]
	s_waitcnt lgkmcnt(0)
	v_mfma_f32_16x16x32_bf16 v[104:107], v[0:3], v[108:111], v[104:107]
	v_add_u32_e32 v0, v53, v70
	v_add_u32_e32 v1, v99, v67
	v_mfma_f32_16x16x32_bf16 v[54:57], v[100:103], v[108:111], v[54:57]
	s_nop 7
	ds_write2st64_b32 v71, v104, v54 offset1:33
	ds_write2st64_b32 v72, v105, v55 offset1:33
	ds_write2st64_b32 v73, v106, v56 offset1:33
	ds_write2st64_b32 v74, v107, v57 offset1:33
	ds_read_b128 v[54:57], v0 offset:17408
	ds_read_b128 v[100:103], v53 offset:37888
	ds_read_b128 v[104:107], v1 offset:27648
	ds_read_b128 v[108:111], v0 offset:18688
	ds_read_b128 v[112:115], v53 offset:37952
	v_mov_b32_e32 v1, 0
	s_waitcnt lgkmcnt(0)
	v_pk_mul_f32 v[32:33], v[32:33], v[100:101]
	v_pk_mul_f32 v[34:35], v[34:35], v[102:103]
	ds_read_b128 v[100:103], v53 offset:38016
	v_pk_mul_f32 v[24:25], v[24:25], v[112:113]
	v_mfma_f32_16x16x32_bf16 v[32:35], v[54:57], v[104:107], v[32:35]
	ds_read_b128 v[54:57], v0 offset:19968
	v_pk_mul_f32 v[26:27], v[26:27], v[114:115]
	s_waitcnt lgkmcnt(0)
	v_pk_mul_f32 v[16:17], v[16:17], v[100:101]
	v_pk_mul_f32 v[18:19], v[18:19], v[102:103]
	v_mfma_f32_16x16x32_bf16 v[24:27], v[108:111], v[104:107], v[24:27]
	ds_read_b128 v[108:111], v0 offset:21248
	ds_read_b128 v[112:115], v53 offset:38080
	s_waitcnt lgkmcnt(0)
	v_pk_mul_f32 v[12:13], v[12:13], v[112:113]
	v_mfma_f32_16x16x32_bf16 v[16:19], v[54:57], v[104:107], v[16:19]
	ds_read_b128 v[54:57], v0 offset:22528
	ds_read_b128 v[100:103], v53 offset:38144
	v_pk_mul_f32 v[14:15], v[14:15], v[114:115]
	s_waitcnt lgkmcnt(0)
	v_pk_mul_f32 v[28:29], v[28:29], v[100:101]
	v_mfma_f32_16x16x32_bf16 v[12:15], v[108:111], v[104:107], v[12:15]
	ds_read_b128 v[108:111], v0 offset:23808
	ds_read_b128 v[112:115], v53 offset:38208
	v_pk_mul_f32 v[30:31], v[30:31], v[102:103]
	ds_read_b128 v[100:103], v0 offset:25088
	s_waitcnt lgkmcnt(0)
	v_pk_mul_f32 v[4:5], v[4:5], v[112:113]
	v_mfma_f32_16x16x32_bf16 v[28:31], v[54:57], v[104:107], v[28:31]
	ds_read_b128 v[54:57], v53 offset:38272
	v_pk_mul_f32 v[6:7], v[6:7], v[114:115]
	ds_read_b128 v[112:115], v0 offset:26368
	s_nop 0
	v_mfma_f32_16x16x32_bf16 v[4:7], v[108:111], v[104:107], v[4:7]
	ds_read_b128 v[108:111], v53 offset:38336
	s_waitcnt lgkmcnt(0)
	v_pk_mul_f32 v[8:9], v[8:9], v[54:55]
	v_pk_mul_f32 v[10:11], v[10:11], v[56:57]
	v_pk_mul_f32 v[20:21], v[20:21], v[108:109]
	s_nop 0
	v_mfma_f32_16x16x32_bf16 v[8:11], v[100:103], v[104:107], v[8:11]
	s_waitcnt vmcnt(0)
	v_add_f32_e32 v103, 0, v90
	v_add_f32_e32 v102, v103, v85
	v_add_f32_e32 v101, v102, v82
	v_add_f32_e32 v100, v101, v91
	v_add_f32_e32 v99, v100, v97
	v_add_f32_e32 v0, v99, v94
	v_add_f32_e32 v53, v0, v93
	v_add_f32_e32 v2, v53, v89
	v_pk_mul_f32 v[22:23], v[22:23], v[110:111]
	ds_write_b32 v59, v2
	s_waitcnt lgkmcnt(0)
	s_barrier
	ds_read2st64_b32 v[56:57], v61 offset1:2
	ds_read2st64_b32 v[54:55], v61 offset0:4 offset1:6
	v_mfma_f32_16x16x32_bf16 v[20:23], v[112:115], v[104:107], v[20:23]
	s_and_saveexec_b64 s[14:15], vcc
	s_cbranch_execz .LBB0_601
	v_cmp_lt_i32_e64 s[50:51], 1, v43
	s_mov_b64 s[28:29], 0
	s_and_saveexec_b64 s[16:17], s[50:51]
	s_xor_b64 s[38:39], exec, s[16:17]
	s_cbranch_execnz .LBB0_603
	s_andn2_saveexec_b64 s[38:39], s[38:39]
	s_cbranch_execnz .LBB0_606

.LBB0_607:
	v_lshl_add_u32 v40, v67, 1, 0
	v_lshl_add_u32 v0, v78, 1, v40
	ds_read_b128 v[36:39], v0 offset:47104
	ds_read_b128 v[48:51], v0 offset:42752
	ds_read_b128 v[52:55], v0 offset:47168
	ds_read_b128 v[76:79], v0 offset:42816
	ds_read_b128 v[86:89], v0 offset:38400
	ds_read_b128 v[90:93], v0 offset:38464
	v_readlane_b32 s4, v243, 45
	s_waitcnt lgkmcnt(0)
	v_mfma_f32_16x16x32_bf16 v[82:85], v[36:39], v[48:51], 0
	s_ashr_i32 s13, s12, 31
	v_mfma_f32_16x16x32_bf16 v[36:39], v[36:39], v[86:89], 0
	ds_read_b128 v[86:89], v0 offset:51456
	ds_read_b128 v[94:97], v0 offset:51520
	s_waitcnt lgkmcnt(0)
	v_mfma_f32_16x16x32_bf16 v[48:51], v[86:89], v[48:51], 0
	ds_read_b128 v[86:89], v0 offset:47232
	ds_read_b128 v[98:101], v0 offset:47296
	ds_read_b128 v[102:105], v0 offset:42880
	ds_read_b128 v[106:109], v0 offset:42944
	ds_read_b128 v[110:113], v0 offset:51584
	ds_read_b128 v[114:117], v0 offset:51648
	ds_read_b128 v[118:121], v0 offset:38528
	ds_read_b128 v[122:125], v0 offset:38592
	v_add_u32_e32 v0, v0, v75
	v_add_u32_e32 v1, 0x9000, v0
	v_mfma_f32_16x16x32_bf16 v[82:85], v[52:55], v[76:79], v[82:85]
	v_cvt_pk_bf16_f32 v126, v32, v33
	v_cvt_pk_bf16_f32 v127, v34, v35
	v_cvt_pk_bf16_f32 v128, v24, v25
	v_mfma_f32_16x16x32_bf16 v[36:39], v[52:55], v[90:93], v[36:39]
	v_cvt_pk_bf16_f32 v129, v26, v27
	ds_read2_b64 v[52:55], v1 offset0:192 offset1:196
	v_add_u32_e32 v0, 0xa000, v0
	v_mfma_f32_16x16x32_bf16 v[48:51], v[94:97], v[76:79], v[48:51]
	ds_read2_b64 v[76:79], v0 offset0:224 offset1:228
	s_waitcnt lgkmcnt(0)
	v_mfma_f32_16x16x32_bf16 v[82:85], v[86:89], v[102:105], v[82:85]
	v_mfma_f32_16x16x32_bf16 v[36:39], v[86:89], v[118:121], v[36:39]
	v_cvt_pk_bf16_f32 v86, v16, v17
	v_cvt_pk_bf16_f32 v87, v18, v19
	v_cvt_pk_bf16_f32 v88, v12, v13
	v_cvt_pk_bf16_f32 v89, v14, v15
	ds_read2_b64 v[90:93], v1 offset0:200 offset1:204
	v_mfma_f32_16x16x32_bf16 v[48:51], v[110:113], v[102:105], v[48:51]
	ds_read2_b64 v[94:97], v0 offset0:232 offset1:236
	v_mfma_f32_16x16x32_bf16 v[82:85], v[98:101], v[106:109], v[82:85]
	v_mfma_f32_16x16x32_bf16 v[36:39], v[98:101], v[122:125], v[36:39]
	v_cvt_pk_bf16_f32 v98, v28, v29
	v_cvt_pk_bf16_f32 v99, v30, v31
	v_cvt_pk_bf16_f32 v100, v4, v5
	v_cvt_pk_bf16_f32 v101, v6, v7
	ds_read2_b64 v[102:105], v1 offset0:208 offset1:212
	v_mfma_f32_16x16x32_bf16 v[52:55], v[52:55], v[126:129], 0
	s_nop 5
	v_cndmask_b32_e64 v2, v38, 0, s[40:41]
	v_mfma_f32_16x16x32_bf16 v[48:51], v[114:117], v[106:109], v[48:51]
	ds_read2_b64 v[106:109], v0 offset0:240 offset1:244
	v_cvt_pk_bf16_f32 v110, v8, v9
	v_cvt_pk_bf16_f32 v111, v10, v11
	v_mfma_f32_16x16x32_bf16 v[76:79], v[76:79], v[126:129], 0
	v_cvt_pk_bf16_f32 v112, v20, v21
	v_cvt_pk_bf16_f32 v113, v22, v23
	ds_read2_b64 v[114:117], v1 offset0:216 offset1:220
	s_waitcnt lgkmcnt(0)
	v_mfma_f32_16x16x32_bf16 v[52:55], v[90:93], v[86:89], v[52:55]
	ds_read2_b64 v[90:93], v0 offset0:248 offset1:252
	v_cndmask_b32_e64 v0, v36, 0, s[46:47]
	s_nop 0
	v_cndmask_b32_e64 v41, v48, 0, s[46:47]
	v_mfma_f32_16x16x32_bf16 v[76:79], v[94:97], v[86:89], v[76:79]
	v_cndmask_b32_e64 v1, 0, v37, s[44:45]
	v_cndmask_b32_e64 v48, v39, 0, s[42:43]
	v_cndmask_b32_e64 v43, 0, v49, s[44:45]
	v_mfma_f32_16x16x32_bf16 v[52:55], v[102:105], v[98:101], v[52:55]
	v_cndmask_b32_e64 v46, v50, 0, s[40:41]
	v_cndmask_b32_e64 v56, v51, 0, s[42:43]
	v_cvt_pk_bf16_f32 v0, v0, v1
	v_mfma_f32_16x16x32_bf16 v[36:39], v[106:109], v[98:101], v[76:79]
	v_cvt_pk_bf16_f32 v1, v2, v48
	v_mov_b32_e32 v2, v3
	v_mfma_f32_16x16x32_bf16 v[48:51], v[114:117], v[110:113], v[52:55]
	v_cvt_pk_bf16_f32 v52, v82, v83
	v_cvt_pk_bf16_f32 v53, v84, v85
	v_cvt_pk_bf16_f32 v54, v41, v43
	v_add3_u32 v41, s4, v69, v80
	v_cvt_pk_bf16_f32 v55, v46, v56
	ds_read2_b64 v[76:79], v41 offset1:4
	s_waitcnt lgkmcnt(0)
	v_mfma_f32_16x16x32_bf16 v[36:39], v[90:93], v[110:113], v[36:39]
	v_readlane_b32 s4, v243, 26
	v_mov_b32_e32 v43, v3
	v_mfma_f32_16x16x32_bf16 v[48:51], v[0:3], v[76:79], v[48:51]
	v_lshl_add_u32 v0, v68, 2, 0
	v_add_u32_e32 v0, 0x12a00, v0
	v_add_u32_e32 v1, v40, v70
	v_mfma_f32_16x16x32_bf16 v[36:39], v[52:55], v[76:79], v[36:39]
	s_nop 7
	ds_write2st64_b32 v71, v48, v36 offset1:33
	ds_write2st64_b32 v72, v49, v37 offset1:33
	ds_write2st64_b32 v73, v50, v38 offset1:33
	ds_write2st64_b32 v74, v51, v39 offset1:33
	ds_read_b128 v[36:39], v0
	ds_read_b128 v[48:51], v1 offset:55808
	v_add_u32_e32 v2, v41, v67
	ds_read_b128 v[52:55], v2
	v_lshlrev_b32_e32 v2, 11, v60
	s_waitcnt lgkmcnt(0)
	v_pk_mul_f32 v[34:35], v[34:35], v[38:39]
	v_pk_mul_f32 v[32:33], v[32:33], v[36:37]
	ds_read_b128 v[36:39], v1 offset:57088
	ds_read_b128 v[68:71], v0 offset:64
	ds_read_b128 v[72:75], v0 offset:448
	v_mfma_f32_16x16x32_bf16 v[32:35], v[48:51], v[52:55], v[32:35]
	ds_read_b128 v[48:51], v1 offset:58368
	ds_read_b128 v[76:79], v0 offset:128
	s_waitcnt lgkmcnt(0)
	v_pk_mul_f32 v[26:27], v[26:27], v[70:71]
	v_pk_mul_f32 v[24:25], v[24:25], v[68:69]
	ds_read_b128 v[68:71], v0 offset:192
	v_pk_mul_f32 v[18:19], v[18:19], v[78:79]
	v_mfma_f32_16x16x32_bf16 v[24:27], v[36:39], v[52:55], v[24:27]
	ds_read_b128 v[36:39], v1 offset:59648
	v_pk_mul_f32 v[16:17], v[16:17], v[76:77]
	s_waitcnt lgkmcnt(0)
	v_pk_mul_f32 v[14:15], v[14:15], v[70:71]
	v_pk_mul_f32 v[12:13], v[12:13], v[68:69]
	v_mfma_f32_16x16x32_bf16 v[16:19], v[48:51], v[52:55], v[16:19]
	ds_read_b128 v[48:51], v1 offset:60928
	ds_read_b128 v[76:79], v0 offset:256
	ds_read_b128 v[68:71], v0 offset:320
	v_pk_mul_f32 v[22:23], v[22:23], v[74:75]
	v_mfma_f32_16x16x32_bf16 v[12:15], v[36:39], v[52:55], v[12:15]
	ds_read_b128 v[36:39], v1 offset:62208
	s_waitcnt lgkmcnt(0)
	v_pk_mul_f32 v[30:31], v[30:31], v[78:79]
	v_pk_mul_f32 v[28:29], v[28:29], v[76:77]
	v_pk_mul_f32 v[6:7], v[6:7], v[70:71]
	v_pk_mul_f32 v[4:5], v[4:5], v[68:69]
	v_mfma_f32_16x16x32_bf16 v[28:31], v[48:51], v[52:55], v[28:31]
	ds_read_b128 v[48:51], v1 offset:63488
	ds_read_b128 v[76:79], v0 offset:384
	v_add_u32_e32 v0, s4, v63
	v_readlane_b32 s4, v244, 7
	v_mfma_f32_16x16x32_bf16 v[4:7], v[36:39], v[52:55], v[4:7]
	ds_read_b128 v[36:39], v1 offset:64768
	v_readlane_b32 s5, v244, 8
	s_add_u32 s8, s6, s4
	v_ashrrev_i32_e32 v1, 31, v0
	s_addc_u32 s9, s7, s5
	s_lshl_b64 s[4:5], s[12:13], 2
	v_lshlrev_b64 v[0:1], 11, v[0:1]
	s_add_u32 s4, s8, s4
	s_waitcnt lgkmcnt(0)
	v_pk_mul_f32 v[10:11], v[10:11], v[78:79]
	v_pk_mul_f32 v[8:9], v[8:9], v[76:77]
	v_pk_mul_f32 v[20:21], v[20:21], v[72:73]
	v_lshl_add_u64 v[0:1], v[44:45], 0, v[0:1]
	s_addc_u32 s5, s9, s5
	v_mfma_f32_16x16x32_bf16 v[8:11], v[48:51], v[52:55], v[8:11]
	s_barrier
	ds_read_b128 v[48:51], v66
	ds_read_b128 v[66:69], v66 offset:16
	v_mfma_f32_16x16x32_bf16 v[20:23], v[36:39], v[52:55], v[20:23]
	s_waitcnt lgkmcnt(0)
	v_cvt_pk_bf16_f32 v36, v48, v49
	v_cvt_pk_bf16_f32 v37, v50, v51
	v_cvt_pk_bf16_f32 v38, v66, v67
	v_cvt_pk_bf16_f32 v39, v68, v69
	global_store_dwordx4 v[0:1], v[36:39], off
	v_lshl_add_u64 v[0:1], s[4:5], 0, v[42:43]
	s_mov_b64 s[4:5], 0x4200000
	v_lshl_add_u64 v[0:1], v[0:1], 0, s[4:5]
	v_lshl_add_u64 v[36:37], v[0:1], 0, v[2:3]
	v_lshlrev_b32_e32 v2, 9, v65
	v_lshl_add_u64 v[38:39], v[0:1], 0, v[2:3]
	v_lshlrev_b32_e32 v2, 9, v64
	s_waitcnt lgkmcnt(0)
	s_barrier
	global_store_dword v[36:37], v32, off
	global_store_dword v[38:39], v33, off
	v_lshl_add_u64 v[32:33], v[0:1], 0, v[2:3]
	v_lshlrev_b32_e32 v2, 9, v62
	v_lshl_add_u64 v[0:1], v[0:1], 0, v[2:3]
	global_store_dword v[0:1], v35, off
	v_add_co_u32_e32 v0, vcc, s36, v36
	s_movk_i32 s4, 0x4000
	s_nop 0
	v_addc_co_u32_e32 v1, vcc, 0, v37, vcc
	global_store_dword v[32:33], v34, off
	global_store_dword v[0:1], v24, off
	global_store_dword v[0:1], v25, off offset:512
	global_store_dword v[0:1], v26, off offset:1024
	global_store_dword v[0:1], v27, off offset:1536
	v_add_co_u32_e32 v0, vcc, s4, v36
	s_movk_i32 s4, 0x6000
	s_nop 0
	v_addc_co_u32_e32 v1, vcc, 0, v37, vcc
	global_store_dword v[0:1], v16, off
	global_store_dword v[0:1], v17, off offset:512
	global_store_dword v[0:1], v18, off offset:1024
	global_store_dword v[0:1], v19, off offset:1536
	v_add_co_u32_e32 v0, vcc, s4, v36
	s_mov_b32 s4, 0x8000
	s_nop 0
	v_addc_co_u32_e32 v1, vcc, 0, v37, vcc
	global_store_dword v[0:1], v12, off
	global_store_dword v[0:1], v13, off offset:512
	global_store_dword v[0:1], v14, off offset:1024
	global_store_dword v[0:1], v15, off offset:1536
	v_add_co_u32_e32 v0, vcc, s4, v36
	s_mov_b32 s4, 0xa000
	s_nop 0
	v_addc_co_u32_e32 v1, vcc, 0, v37, vcc
	global_store_dword v[0:1], v28, off
	global_store_dword v[0:1], v29, off offset:512
	global_store_dword v[0:1], v30, off offset:1024
	global_store_dword v[0:1], v31, off offset:1536
	v_add_co_u32_e32 v0, vcc, s4, v36
	s_mov_b32 s4, 0xc000
	s_nop 0
	v_addc_co_u32_e32 v1, vcc, 0, v37, vcc
	global_store_dword v[0:1], v4, off
	global_store_dword v[0:1], v5, off offset:512
	global_store_dword v[0:1], v6, off offset:1024
	global_store_dword v[0:1], v7, off offset:1536
	v_add_co_u32_e32 v0, vcc, s4, v36
	s_nop 1
	v_addc_co_u32_e32 v1, vcc, 0, v37, vcc
	global_store_dword v[0:1], v8, off
	global_store_dword v[0:1], v9, off offset:512
	global_store_dword v[0:1], v10, off offset:1024
	global_store_dword v[0:1], v11, off offset:1536
	v_add_co_u32_e32 v0, vcc, 0xe000, v36
	s_nop 1
	v_addc_co_u32_e32 v1, vcc, 0, v37, vcc
	global_store_dword v[0:1], v20, off
	global_store_dword v[0:1], v21, off offset:512
	global_store_dword v[0:1], v22, off offset:1024
	global_store_dword v[0:1], v23, off offset:1536
	s_and_saveexec_b64 s[4:5], s[0:1]
	s_cbranch_execz .LBB0_609
	v_mul_f32_e32 v0, 0x3fb8aa3b, v47
	v_readlane_b32 s0, v244, 6
	v_exp_f32_e32 v2, v0
	s_nop 0
	v_or_b32_e32 v0, s0, v58
	v_ashrrev_i32_e32 v1, 31, v0
	v_lshl_add_u64 v[0:1], v[0:1], 2, s[6:7]
	v_add_co_u32_e32 v0, vcc, 0x5200000, v0
	s_nop 1
	v_addc_co_u32_e32 v1, vcc, 0, v1, vcc
	global_store_dword v[0:1], v2, off
